# v22 state (without the SGU main-step hoist) for comparison
# baseline (speedup 1.0000x reference)
.LBB0_880:
	s_mov_b64 s[0:1], s[88:89]
	s_mov_b32 s8, s67
	s_mov_b32 s2, s68
	s_mov_b32 s6, s76
	v_mov_b32_e32 v0, v213
	s_waitcnt vmcnt(0)
	s_barrier
	s_cmp_lt_i32 s2, 0
	v_readfirstlane_b32 s3, v0
	s_cbranch_scc1 .LBB0_948
	s_lshl_b32 s4, s2, 3
	s_ashr_i32 s2, s3, 6
	s_add_i32 s10, s2, s4
	s_sub_i32 s10, 0x7ff, s10
	s_cmpk_gt_i32 s10, 0xa3f
	s_cbranch_scc1 .LBB0_948
	s_load_dwordx2 s[4:5], s[0:1], 0xb8
	v_lshlrev_b32_e32 v1, 2, v0
	v_bfe_u32 v77, v0, 4, 2
	v_bfe_u32 v79, v0, 3, 3
	v_lshlrev_b32_e32 v0, 3, v0
	s_mulk_i32 s2, 0x4100
	v_and_b32_e32 v76, 60, v1
	v_and_b32_e32 v0, 56, v0
	s_add_i32 s9, s2, 0
	v_lshlrev_b32_e32 v1, 2, v76
	v_mul_u32_u24_e32 v2, 0x104, v77
	v_lshlrev_b32_e32 v168, 1, v0
	v_add3_u32 v78, s9, v1, v2
	v_mul_u32_u24_e32 v2, 0x104, v0
	s_waitcnt lgkmcnt(0)
	v_lshl_add_u64 v[0:1], s[4:5], 0, v[168:169]
	s_mov_b64 s[12:13], 0x2d00000
	s_ashr_i32 s7, s6, 31
	s_mov_b64 s[4:5], 0x2e00000
	v_lshl_add_u64 v[66:67], v[0:1], 0, s[12:13]
	s_mov_b64 s[12:13], 0x2c00000
	s_mov_b64 s[14:15], 0x2680000
	s_lshl_b64 s[2:3], s[6:7], 22
	v_lshl_add_u64 v[64:65], v[0:1], 0, s[4:5]
	s_lshl_b64 s[4:5], s[6:7], 21
	v_lshl_add_u64 v[68:69], v[0:1], 0, s[12:13]
	s_mul_hi_i32 s12, s6, 0xb00000
	s_mul_i32 s13, s6, 0xb00000
	v_lshl_add_u64 v[70:71], v[0:1], 0, s[14:15]
	s_mul_hi_i32 s14, s6, 0x1600000
	s_mul_i32 s15, s6, 0x1600000
	s_mov_b64 s[6:7], 0x1b80000
	v_lshlrev_b32_e32 v3, 2, v79
	v_lshl_add_u64 v[72:73], v[0:1], 0, s[6:7]
	s_lshl_b32 s6, s10, 2
	s_lshl_b32 s11, s8, 3
	v_add3_u32 v80, s9, v2, v3
	v_or_b32_e32 v81, 8, v79
	v_or_b32_e32 v82, 16, v79
	v_or_b32_e32 v83, 24, v79
	v_or_b32_e32 v84, 32, v79
	v_or_b32_e32 v85, 40, v79
	v_or_b32_e32 v86, 48, v79
	v_or_b32_e32 v87, 56, v79
	s_lshl_b32 s16, s10, 6
	s_lshl_b32 s17, s8, 9
	s_add_i32 s18, s6, 0x3ea00
	s_lshl_b32 s19, s8, 5
	s_branch .LBB0_885

.LBB0_1004:
	s_bfe_u32 s22, s21, 0x30005
	s_cmpk_gt_u32 s21, 0xff
	s_cselect_b64 s[12:13], -1, 0
	s_and_b32 s14, s21, 0xffffff00
	s_add_i32 s16, s14, s18
	s_cmpk_lt_u32 s21, 0x100
	s_mov_b32 s14, 0x1c700000
	s_cselect_b32 s17, s14, 0x1cf00000
	s_movk_i32 s14, 0x48
	s_cselect_b32 s14, s14, 0x58
	s_add_u32 s14, s2, s14
	s_addc_u32 s15, s3, 0
	s_load_dwordx2 s[14:15], s[14:15], 0x0
	s_waitcnt lgkmcnt(0)
	s_barrier
	s_add_u32 s14, s14, s10
	s_addc_u32 s15, s15, s11
	v_lshl_add_u64 v[12:13], v[4:5], 4, s[14:15]
	global_load_dwordx4 v[0:3], v[12:13], off
	s_movk_i32 s14, 0x6000
	v_add_co_u32_e32 v116, vcc, s69, v12
	s_nop 1
	v_addc_co_u32_e32 v117, vcc, 0, v13, vcc
	global_load_dwordx4 v[120:123], v[116:117], off
	v_add_co_u32_e32 v118, vcc, s81, v12
	s_nop 1
	v_addc_co_u32_e32 v119, vcc, 0, v13, vcc
	global_load_dwordx4 v[124:127], v[118:119], off
	v_add_co_u32_e32 v116, vcc, s14, v12
	s_mov_b32 s14, 0xa000
	s_nop 0
	v_addc_co_u32_e32 v117, vcc, 0, v13, vcc
	global_load_dwordx4 v[128:131], v[116:117], off
	v_add_co_u32_e32 v118, vcc, s84, v12
	s_nop 1
	v_addc_co_u32_e32 v119, vcc, 0, v13, vcc
	global_load_dwordx4 v[132:135], v[118:119], off
	v_add_co_u32_e32 v116, vcc, s14, v12
	s_mov_b32 s14, 0xe000
	s_nop 0
	v_addc_co_u32_e32 v117, vcc, 0, v13, vcc
	global_load_dwordx4 v[136:139], v[116:117], off
	v_add_co_u32_e32 v118, vcc, s85, v12
	s_nop 1
	v_addc_co_u32_e32 v119, vcc, 0, v13, vcc
	global_load_dwordx4 v[140:143], v[118:119], off
	v_add_co_u32_e32 v116, vcc, s14, v12
	s_add_u32 s14, s4, s17
	s_nop 0
	v_addc_co_u32_e32 v117, vcc, 0, v13, vcc
	global_load_dwordx4 v[144:147], v[116:117], off
	s_addc_u32 s15, s5, 0
	s_lshl_b32 s23, s21, 4
	s_and_b32 s23, s23, 0x1f0
	v_add_u32_e32 v12, s23, v17
	s_lshl_b32 s76, s22, 9
	v_ashrrev_i32_e32 v13, 31, v12
	s_ashr_i32 s17, s16, 31
	s_waitcnt vmcnt(7)
	ds_write_b128 v15, v[0:3] offset:16384
	s_waitcnt vmcnt(6)
	ds_write_b128 v15, v[120:123] offset:24576
	s_waitcnt vmcnt(5)
	ds_write_b128 v15, v[124:127] offset:32768
	s_waitcnt vmcnt(4)
	ds_write_b128 v15, v[128:131] offset:40960
	s_waitcnt vmcnt(3)
	ds_write_b128 v15, v[132:135] offset:49152
	s_waitcnt vmcnt(2)
	ds_write_b128 v15, v[136:139] offset:57344
	s_waitcnt vmcnt(1)
	ds_write_b128 v16, v[140:143] offset:49152
	s_waitcnt vmcnt(0)
	ds_write_b128 v16, v[144:147] offset:57344
	v_lshl_add_u64 v[2:3], s[16:17], 2, v[6:7]
	global_load_dword v2, v[2:3], off
	v_mov_b32_e32 v150, v12
	v_lshl_add_u64 v[0:1], v[12:13], 0, s[76:77]
	v_lshlrev_b64 v[0:1], 11, v[0:1]
	v_lshl_add_u64 v[0:1], s[14:15], 0, v[0:1]
	v_lshl_add_u64 v[0:1], v[0:1], 0, v[168:169]
	global_load_dword v110, v[0:1], off
	global_load_dword v120, v[0:1], off offset:3072
	v_add_u32_e32 v12, s23, v18
	v_ashrrev_i32_e32 v13, 31, v12
	v_mov_b32_e32 v151, v12
	v_lshl_add_u64 v[0:1], v[12:13], 0, s[76:77]
	v_lshlrev_b64 v[0:1], 11, v[0:1]
	v_lshl_add_u64 v[0:1], s[14:15], 0, v[0:1]
	v_lshl_add_u64 v[0:1], v[0:1], 0, v[168:169]
	global_load_dword v111, v[0:1], off
	global_load_dword v121, v[0:1], off offset:3072
	v_add_u32_e32 v12, s23, v19
	v_ashrrev_i32_e32 v13, 31, v12
	v_mov_b32_e32 v152, v12
	v_lshl_add_u64 v[0:1], v[12:13], 0, s[76:77]
	v_lshlrev_b64 v[0:1], 11, v[0:1]
	v_lshl_add_u64 v[0:1], s[14:15], 0, v[0:1]
	v_lshl_add_u64 v[0:1], v[0:1], 0, v[168:169]
	global_load_dword v112, v[0:1], off
	global_load_dword v122, v[0:1], off offset:3072
	v_add_u32_e32 v12, s23, v20
	v_ashrrev_i32_e32 v13, 31, v12
	v_mov_b32_e32 v153, v12
	v_lshl_add_u64 v[0:1], v[12:13], 0, s[76:77]
	v_lshlrev_b64 v[0:1], 11, v[0:1]
	v_lshl_add_u64 v[0:1], s[14:15], 0, v[0:1]
	v_lshl_add_u64 v[0:1], v[0:1], 0, v[168:169]
	global_load_dword v113, v[0:1], off
	global_load_dword v123, v[0:1], off offset:3072
	v_add_u32_e32 v12, s23, v21
	v_ashrrev_i32_e32 v13, 31, v12
	v_mov_b32_e32 v154, v12
	v_lshl_add_u64 v[0:1], v[12:13], 0, s[76:77]
	v_lshlrev_b64 v[0:1], 11, v[0:1]
	v_lshl_add_u64 v[0:1], s[14:15], 0, v[0:1]
	v_lshl_add_u64 v[0:1], v[0:1], 0, v[168:169]
	global_load_dword v114, v[0:1], off
	global_load_dword v124, v[0:1], off offset:3072
	v_add_u32_e32 v12, s23, v22
	v_ashrrev_i32_e32 v13, 31, v12
	v_mov_b32_e32 v155, v12
	v_lshl_add_u64 v[0:1], v[12:13], 0, s[76:77]
	v_lshlrev_b64 v[0:1], 11, v[0:1]
	v_lshl_add_u64 v[0:1], s[14:15], 0, v[0:1]
	v_lshl_add_u64 v[0:1], v[0:1], 0, v[168:169]
	global_load_dword v115, v[0:1], off
	global_load_dword v125, v[0:1], off offset:3072
	v_add_u32_e32 v12, s23, v23
	v_ashrrev_i32_e32 v13, 31, v12
	v_mov_b32_e32 v156, v12
	v_lshl_add_u64 v[0:1], v[12:13], 0, s[76:77]
	v_lshlrev_b64 v[0:1], 11, v[0:1]
	v_lshl_add_u64 v[0:1], s[14:15], 0, v[0:1]
	v_lshl_add_u64 v[0:1], v[0:1], 0, v[168:169]
	global_load_dword v116, v[0:1], off
	global_load_dword v126, v[0:1], off offset:3072
	v_add_u32_e32 v12, s23, v24
	v_ashrrev_i32_e32 v13, 31, v12
	v_mov_b32_e32 v157, v12
	v_lshl_add_u64 v[0:1], v[12:13], 0, s[76:77]
	v_lshlrev_b64 v[0:1], 11, v[0:1]
	v_lshl_add_u64 v[0:1], s[14:15], 0, v[0:1]
	v_lshl_add_u64 v[0:1], v[0:1], 0, v[168:169]
	global_load_dword v117, v[0:1], off
	global_load_dword v127, v[0:1], off offset:3072
	s_waitcnt vmcnt(0)
	v_add_f32_e32 v3, v2, v110
	s_movk_i32 s16, 0x1ff
	v_cmp_gt_i32_e32 vcc, s16, v150
	s_and_saveexec_b64 s[16:17], vcc
	v_add_f32_e32 v3, v3, v120
	s_or_b64 exec, exec, s[16:17]
	v_mul_f32_e32 v0, 0x3d372713, v3
	v_mul_f32_e32 v0, v3, v0
	v_fma_f32 v0, v3, v0, v3
	v_mul_f32_e32 v0, 0x3f4c422a, v0
	v_add_f32_e32 v0, v0, v0
	v_mul_f32_e32 v0, 0xbfb8aa3b, v0
	v_exp_f32_e32 v0, v0
	s_nop 0
	v_add_f32_e32 v0, 1.0, v0
	v_rcp_f32_e32 v0, v0
	s_nop 0
	v_mul_f32_e32 v0, v3, v0
	ds_write_b32 v26, v0
	v_add_f32_e32 v3, v2, v111
	s_movk_i32 s16, 0x1ff
	v_cmp_gt_i32_e32 vcc, s16, v151
	s_and_saveexec_b64 s[16:17], vcc
	v_add_f32_e32 v3, v3, v121
	s_or_b64 exec, exec, s[16:17]
	v_mul_f32_e32 v0, 0x3d372713, v3
	v_mul_f32_e32 v0, v3, v0
	v_fma_f32 v0, v3, v0, v3
	v_mul_f32_e32 v0, 0x3f4c422a, v0
	v_add_f32_e32 v0, v0, v0
	v_mul_f32_e32 v0, 0xbfb8aa3b, v0
	v_exp_f32_e32 v0, v0
	s_nop 0
	v_add_f32_e32 v0, 1.0, v0
	v_rcp_f32_e32 v0, v0
	s_nop 0
	v_mul_f32_e32 v0, v3, v0
	ds_write_b32 v26, v0 offset:2048
	v_add_f32_e32 v3, v2, v112
	s_movk_i32 s16, 0x1ff
	v_cmp_gt_i32_e32 vcc, s16, v152
	s_and_saveexec_b64 s[16:17], vcc
	v_add_f32_e32 v3, v3, v122
	s_or_b64 exec, exec, s[16:17]
	v_mul_f32_e32 v0, 0x3d372713, v3
	v_mul_f32_e32 v0, v3, v0
	v_fma_f32 v0, v3, v0, v3
	v_mul_f32_e32 v0, 0x3f4c422a, v0
	v_add_f32_e32 v0, v0, v0
	v_mul_f32_e32 v0, 0xbfb8aa3b, v0
	v_exp_f32_e32 v0, v0
	s_nop 0
	v_add_f32_e32 v0, 1.0, v0
	v_rcp_f32_e32 v0, v0
	s_nop 0
	v_mul_f32_e32 v0, v3, v0
	ds_write_b32 v26, v0 offset:4096
	v_add_f32_e32 v3, v2, v113
	s_movk_i32 s16, 0x1ff
	v_cmp_gt_i32_e32 vcc, s16, v153
	s_and_saveexec_b64 s[16:17], vcc
	v_add_f32_e32 v3, v3, v123
	s_or_b64 exec, exec, s[16:17]
	v_mul_f32_e32 v0, 0x3d372713, v3
	v_mul_f32_e32 v0, v3, v0
	v_fma_f32 v0, v3, v0, v3
	v_mul_f32_e32 v0, 0x3f4c422a, v0
	v_add_f32_e32 v0, v0, v0
	v_mul_f32_e32 v0, 0xbfb8aa3b, v0
	v_exp_f32_e32 v0, v0
	s_nop 0
	v_add_f32_e32 v0, 1.0, v0
	v_rcp_f32_e32 v0, v0
	s_nop 0
	v_mul_f32_e32 v0, v3, v0
	ds_write_b32 v26, v0 offset:6144
	v_add_f32_e32 v3, v2, v114
	s_movk_i32 s16, 0x1ff
	v_cmp_gt_i32_e32 vcc, s16, v154
	s_and_saveexec_b64 s[16:17], vcc
	v_add_f32_e32 v3, v3, v124
	s_or_b64 exec, exec, s[16:17]
	v_mul_f32_e32 v0, 0x3d372713, v3
	v_mul_f32_e32 v0, v3, v0
	v_fma_f32 v0, v3, v0, v3
	v_mul_f32_e32 v0, 0x3f4c422a, v0
	v_add_f32_e32 v0, v0, v0
	v_mul_f32_e32 v0, 0xbfb8aa3b, v0
	v_exp_f32_e32 v0, v0
	s_nop 0
	v_add_f32_e32 v0, 1.0, v0
	v_rcp_f32_e32 v0, v0
	s_nop 0
	v_mul_f32_e32 v0, v3, v0
	ds_write_b32 v26, v0 offset:8192
	v_add_f32_e32 v3, v2, v115
	s_movk_i32 s16, 0x1ff
	v_cmp_gt_i32_e32 vcc, s16, v155
	s_and_saveexec_b64 s[16:17], vcc
	v_add_f32_e32 v3, v3, v125
	s_or_b64 exec, exec, s[16:17]
	v_mul_f32_e32 v0, 0x3d372713, v3
	v_mul_f32_e32 v0, v3, v0
	v_fma_f32 v0, v3, v0, v3
	v_mul_f32_e32 v0, 0x3f4c422a, v0
	v_add_f32_e32 v0, v0, v0
	v_mul_f32_e32 v0, 0xbfb8aa3b, v0
	v_exp_f32_e32 v0, v0
	s_nop 0
	v_add_f32_e32 v0, 1.0, v0
	v_rcp_f32_e32 v0, v0
	s_nop 0
	v_mul_f32_e32 v0, v3, v0
	ds_write_b32 v26, v0 offset:10240
	v_add_f32_e32 v3, v2, v116
	s_movk_i32 s16, 0x1ff
	v_cmp_gt_i32_e32 vcc, s16, v156
	s_and_saveexec_b64 s[16:17], vcc
	v_add_f32_e32 v3, v3, v126
	s_or_b64 exec, exec, s[16:17]
	v_mul_f32_e32 v0, 0x3d372713, v3
	v_mul_f32_e32 v0, v3, v0
	v_fma_f32 v0, v3, v0, v3
	v_mul_f32_e32 v0, 0x3f4c422a, v0
	v_add_f32_e32 v0, v0, v0
	v_mul_f32_e32 v0, 0xbfb8aa3b, v0
	v_exp_f32_e32 v0, v0
	s_nop 0
	v_add_f32_e32 v0, 1.0, v0
	v_rcp_f32_e32 v0, v0
	s_nop 0
	v_mul_f32_e32 v0, v3, v0
	ds_write_b32 v26, v0 offset:12288
	v_add_f32_e32 v3, v2, v117
	s_movk_i32 s16, 0x1ff
	v_cmp_gt_i32_e32 vcc, s16, v157
	s_and_saveexec_b64 s[16:17], vcc
	v_add_f32_e32 v3, v3, v127
	s_or_b64 exec, exec, s[16:17]
	v_mul_f32_e32 v0, 0x3d372713, v3
	v_mul_f32_e32 v0, v3, v0
	v_fma_f32 v0, v3, v0, v3
	v_mul_f32_e32 v0, 0x3f4c422a, v0
	v_add_f32_e32 v0, v0, v0
	v_mul_f32_e32 v0, 0xbfb8aa3b, v0
	v_exp_f32_e32 v0, v0
	s_nop 0
	v_add_f32_e32 v0, 1.0, v0
	v_rcp_f32_e32 v0, v0
	s_nop 0
	v_mul_f32_e32 v0, v3, v0
	ds_write_b32 v26, v0 offset:14336
	v_mov_b32_e32 v12, 0
	s_lshr_b32 s16, s21, 5
	s_mov_b32 s14, 0
	v_mov_b32_e32 v27, v25
	v_mov_b32_e32 v13, v12
	s_waitcnt lgkmcnt(0)
	s_barrier
